# k17 with the GEMM1 code touch in the last two iterations and its window starting 4 KB before the loop entry
# baseline (speedup 1.0000x reference)
.LBB0_241:
	s_ashr_i32 s75, s74, 31
	s_lshl_b64 s[22:23], s[74:75], 19
	s_add_u32 s68, s10, s22
	s_addc_u32 s69, s11, s23
	s_and_b64 s[22:23], s[36:37], exec
	s_cselect_b32 s22, s69, s1
	s_cselect_b32 s23, s68, s0
	s_ashr_i32 s7, s6, 31
	s_lshl_b64 s[38:39], s[6:7], 19
	s_add_u32 s80, s89, s38
	s_addc_u32 s81, s91, s39
	s_and_b64 s[36:37], s[36:37], exec
	s_cselect_b32 s7, s81, s5
	s_cselect_b32 s25, s80, s4
	s_add_u32 s0, s0, 0x40080
	s_addc_u32 s1, s1, 0
	s_add_u32 s38, s4, 0x100
	v_mov_b32_e32 v0, 0
	s_addc_u32 s39, s5, 0
	s_mov_b32 s75, -2
	s_waitcnt lgkmcnt(0)
	v_mov_b32_e32 v1, v0
	v_mov_b32_e32 v2, v0
	v_mov_b32_e32 v3, v0
	v_mov_b32_e32 v4, v0
	v_mov_b32_e32 v5, v0
	v_mov_b32_e32 v6, v0
	v_mov_b32_e32 v7, v0
	v_mov_b32_e32 v16, v0
	v_mov_b32_e32 v17, v0
	v_mov_b32_e32 v18, v0
	v_mov_b32_e32 v19, v0
	v_mov_b32_e32 v20, v0
	v_mov_b32_e32 v21, v0
	v_mov_b32_e32 v22, v0
	v_mov_b32_e32 v23, v0
	v_mov_b32_e32 v32, v0
	v_mov_b32_e32 v33, v0
	v_mov_b32_e32 v34, v0
	v_mov_b32_e32 v35, v0
	v_mov_b32_e32 v36, v0
	v_mov_b32_e32 v37, v0
	v_mov_b32_e32 v38, v0
	v_mov_b32_e32 v39, v0
	v_mov_b32_e32 v48, v0
	v_mov_b32_e32 v49, v0
	v_mov_b32_e32 v50, v0
	v_mov_b32_e32 v51, v0
	v_mov_b32_e32 v52, v0
	v_mov_b32_e32 v53, v0
	v_mov_b32_e32 v54, v0
	v_mov_b32_e32 v55, v0
	v_mov_b32_e32 v8, v0
	v_mov_b32_e32 v9, v0
	v_mov_b32_e32 v10, v0
	v_mov_b32_e32 v11, v0
	v_mov_b32_e32 v12, v0
	v_mov_b32_e32 v13, v0
	v_mov_b32_e32 v14, v0
	v_mov_b32_e32 v15, v0
	v_mov_b32_e32 v24, v0
	v_mov_b32_e32 v25, v0
	v_mov_b32_e32 v26, v0
	v_mov_b32_e32 v27, v0
	v_mov_b32_e32 v28, v0
	v_mov_b32_e32 v29, v0
	v_mov_b32_e32 v30, v0
	v_mov_b32_e32 v31, v0
	v_mov_b32_e32 v40, v0
	v_mov_b32_e32 v41, v0
	v_mov_b32_e32 v42, v0
	v_mov_b32_e32 v43, v0
	v_mov_b32_e32 v44, v0
	v_mov_b32_e32 v45, v0
	v_mov_b32_e32 v46, v0
	v_mov_b32_e32 v47, v0
	v_mov_b32_e32 v56, v0
	v_mov_b32_e32 v57, v0
	v_mov_b32_e32 v58, v0
	v_mov_b32_e32 v59, v0
	v_mov_b32_e32 v60, v0
	v_mov_b32_e32 v61, v0
	v_mov_b32_e32 v62, v0
	v_mov_b32_e32 v63, v0
	v_mov_b32_e32 v64, v0
	v_mov_b32_e32 v65, v0
	v_mov_b32_e32 v66, v0
	v_mov_b32_e32 v67, v0
	v_mov_b32_e32 v68, v0
	v_mov_b32_e32 v69, v0
	v_mov_b32_e32 v70, v0
	v_mov_b32_e32 v71, v0
	v_mov_b32_e32 v80, v0
	v_mov_b32_e32 v81, v0
	v_mov_b32_e32 v82, v0
	v_mov_b32_e32 v83, v0
	v_mov_b32_e32 v84, v0
	v_mov_b32_e32 v85, v0
	v_mov_b32_e32 v86, v0
	v_mov_b32_e32 v87, v0
	v_mov_b32_e32 v96, v0
	v_mov_b32_e32 v97, v0
	v_mov_b32_e32 v98, v0
	v_mov_b32_e32 v99, v0
	v_mov_b32_e32 v100, v0
	v_mov_b32_e32 v101, v0
	v_mov_b32_e32 v102, v0
	v_mov_b32_e32 v103, v0
	v_mov_b32_e32 v112, v0
	v_mov_b32_e32 v113, v0
	v_mov_b32_e32 v114, v0
	v_mov_b32_e32 v115, v0
	v_mov_b32_e32 v116, v0
	v_mov_b32_e32 v117, v0
	v_mov_b32_e32 v118, v0
	v_mov_b32_e32 v119, v0
	v_mov_b32_e32 v72, v0
	v_mov_b32_e32 v73, v0
	v_mov_b32_e32 v74, v0
	v_mov_b32_e32 v75, v0
	v_mov_b32_e32 v76, v0
	v_mov_b32_e32 v77, v0
	v_mov_b32_e32 v78, v0
	v_mov_b32_e32 v79, v0
	v_mov_b32_e32 v88, v0
	v_mov_b32_e32 v89, v0
	v_mov_b32_e32 v90, v0
	v_mov_b32_e32 v91, v0
	v_mov_b32_e32 v92, v0
	v_mov_b32_e32 v93, v0
	v_mov_b32_e32 v94, v0
	v_mov_b32_e32 v95, v0
	v_mov_b32_e32 v104, v0
	v_mov_b32_e32 v105, v0
	v_mov_b32_e32 v106, v0
	v_mov_b32_e32 v107, v0
	v_mov_b32_e32 v108, v0
	v_mov_b32_e32 v109, v0
	v_mov_b32_e32 v110, v0
	v_mov_b32_e32 v111, v0
	v_mov_b32_e32 v120, v0
	v_mov_b32_e32 v121, v0
	v_mov_b32_e32 v122, v0
	v_mov_b32_e32 v123, v0
	v_mov_b32_e32 v124, v0
	v_mov_b32_e32 v125, v0
	v_mov_b32_e32 v126, v0
	v_mov_b32_e32 v127, v0
	s_getpc_b64 s[98:99]
	s_sub_u32 s98, s98, 0x1000
	s_subb_u32 s99, s99, 0
	v_lshlrev_b32_e32 v246, 7, v202
	v_mov_b32_e32 v247, 0
	v_lshl_add_u64 v[246:247], v[246:247], 0, s[98:99]
.LBB0_242:
	s_add_u32 s4, s0, 0xfffc0080
	s_addc_u32 s5, s1, -1
	s_add_i32 vcc_lo, 0, 0x10000
	v_add_u32_e32 v128, vcc_lo, v162
	ds_read_b128 v[142:145], v128
	ds_read_b128 v[146:149], v128 offset:1024
	ds_read_b128 v[150:153], v128 offset:2048
	ds_read_b128 v[154:157], v128 offset:3072
	s_cmp_eq_u32 s75, 12
	s_cselect_b32 s37, s22, s5
	s_cselect_b32 s36, s23, s4
	s_cselect_b32 s5, s7, s39
	s_cselect_b32 s4, s25, s38
	v_lshl_add_u64 v[196:197], s[0:1], 0, v[138:139]
	s_add_i32 m0, s95, 0xc000
	ds_read_b128 v[164:167], v163
	ds_read_b128 v[168:171], v163 offset:1024
	ds_read_b128 v[172:175], v163 offset:2048
	ds_read_b128 v[176:179], v163 offset:3072
	ds_read_b128 v[180:183], v163 offset:4096
	ds_read_b128 v[184:187], v163 offset:5120
	ds_read_b128 v[188:191], v163 offset:6144
	ds_read_b128 v[192:195], v163 offset:7168
	global_load_lds_dwordx4 v[196:197], off
	v_lshl_add_u64 v[196:197], s[0:1], 0, v[140:141]
	s_add_i32 m0, s95, 0xe000
	s_nop 0
	global_load_lds_dwordx4 v[196:197], off
	s_cmp_ge_i32 s75, 10
	s_cbranch_scc0 .Lct_skip
	global_load_dword v248, v[246:247], off
